# rg_conv rewritten by hand: all 19 row loads issued first (halo rows behind wave-uniform branches), sliding window of unpacked rows, same fma order
# speedup vs baseline: 1.0092x; 1.0092x over previous
; #define TIDX tid_opaque()
; __device__ __forceinline__ u32x4 zero4() { unsigned z = 0; asm volatile("" : "+v"(z)); return (u32x4){z, z, z, z}; }
; __device__ __forceinline__ unsigned cvt_pk_bf16(float lo, float hi) { const f32x2_t v = {lo, hi}; const bf16x2_t b = __builtin_convertvector(v, bf16x2_t); return __builtin_bit_cast(unsigned, b); }
; __device__ void rg_conv_phase(const Params& p, int l) {
;     const bf16_t* urg = (const bf16_t*)(((unsigned char*)ldp(38)) + OFF_A + 96 * MiB); bf16_t* xc = (bf16_t*)(((unsigned char*)ldp(38)) + OFF_XC);
;     const float* cw = ((const float*)ldp(19)) + (size_t)l * 4 * RGW; const float* cb = ((const float*)ldp(20)) + (size_t)l * RGW;
;     const int total = (MT / 16) * 64;
;     for (int idx = blockIdx.x * 512 + TIDX; idx < total; idx += gridDim.x * 512) {
;         const int c8 = idx & 63, run = idx >> 6, tok0 = run * 16, t0 = tok0 & (SEQ - 1);
;         float wgt[4][8], bia[8];
; #pragma unroll
;         for (int i = 0; i < 8; ++i) { bia[i] = cb[c8 * 8 + i];
; #pragma unroll
;             for (int k = 0; k < 4; ++k) wgt[k][i] = cw[k * RGW + c8 * 8 + i]; }
;         u32x4 win[4];
;         const bf16_t* src = urg + (size_t)tok0 * 1024 + c8 * 8;
; #pragma unroll
;         for (int k = 0; k < 3; ++k) { const int tt = t0 + k - 2; win[k + 1] = (tt >= 0 && tt < SEQ) ? *(const u32x4*)(src + (ptrdiff_t)(k - 2) * 1024) : zero4(); }
; #pragma unroll
;         for (int i = 0; i < 16; ++i) {
;             win[0] = win[1]; win[1] = win[2]; win[2] = win[3];
;             { const int tt = t0 + i + 1; win[3] = (tt < SEQ) ? *(const u32x4*)(src + (ptrdiff_t)(i + 1) * 1024) : zero4(); }
;             float a[8];
; #pragma unroll
;             for (int e = 0; e < 8; ++e) a[e] = bia[e];
; #pragma unroll
;             for (int k = 0; k < 4; ++k) { const u32x4 xv = win[k];
;                 a[0] += wgt[k][0] * lo_bf(xv.x); a[1] += wgt[k][1] * hi_bf(xv.x); a[2] += wgt[k][2] * lo_bf(xv.y); a[3] += wgt[k][3] * hi_bf(xv.y);
;                 a[4] += wgt[k][4] * lo_bf(xv.z); a[5] += wgt[k][5] * hi_bf(xv.z); a[6] += wgt[k][6] * lo_bf(xv.w); a[7] += wgt[k][7] * hi_bf(xv.w); }
;             u32x4 w; w.x = cvt_pk_bf16(a[0], a[1]); w.y = cvt_pk_bf16(a[2], a[3]); w.z = cvt_pk_bf16(a[4], a[5]); w.w = cvt_pk_bf16(a[6], a[7]);
;             *(u32x4*)(xc + (size_t)(tok0 + i) * 512 + c8 * 8) = w;
.LBB0_262:
	v_and_b32_e32 v42, 0x1f8, v73
	v_lshlrev_b32_e32 v184, 2, v42
	v_lshl_add_u64 v[12:13], s[10:11], 0, v[184:185]
	s_mov_b64 s[18:19], 0x1000
	v_lshl_add_u64 v[14:15], v[12:13], 0, s[18:19]
	s_mov_b64 s[18:19], 0x1800
	v_lshl_add_u64 v[40:41], v[12:13], 0, s[18:19]
	global_load_dwordx4 v[0:3], v184, s[12:13] offset:16
	global_load_dwordx4 v[20:23], v184, s[12:13]
	global_load_dwordx4 v[4:7], v184, s[10:11] offset:16
	global_load_dwordx4 v[24:27], v184, s[10:11]
	global_load_dwordx4 v[8:11], v184, s[10:11] offset:2064
	global_load_dwordx4 v[28:31], v184, s[10:11] offset:2048
	v_add_co_u32_e32 v12, vcc, s78, v12
	v_ashrrev_i32_e32 v74, 2, v72
	s_nop 0
	v_addc_co_u32_e32 v13, vcc, 0, v13, vcc
	global_load_dwordx4 v[36:39], v[12:13], off
	global_load_dwordx4 v[32:35], v[12:13], off offset:2048
	global_load_dwordx4 v[16:19], v[14:15], off offset:16
	s_nop 0
	global_load_dwordx4 v[12:15], v[40:41], off offset:16
	v_and_b32_e32 v52, -16, v74
	v_ashrrev_i32_e32 v53, 31, v52
	v_lshlrev_b64 v[40:41], 11, v[52:53]
	v_and_b32_e32 v75, 0x7f0, v74
	v_lshl_add_u64 v[40:41], s[6:7], 0, v[40:41]
	v_lshlrev_b32_e32 v184, 1, v42
	v_lshl_add_u64 v[48:49], v[40:41], 0, v[184:185]
	v_cmp_ne_u32_e32 vcc, 0, v75
	v_mov_b32_e32 v40, 0
	v_mov_b32_e32 v41, 0
	v_mov_b32_e32 v42, 0
	v_mov_b32_e32 v43, 0
	v_mov_b32_e32 v44, 0
	v_mov_b32_e32 v45, 0
	v_mov_b32_e32 v46, 0
	v_mov_b32_e32 v47, 0
	v_mov_b32_e32 v142, 0
	v_mov_b32_e32 v143, 0
	v_mov_b32_e32 v144, 0
	v_mov_b32_e32 v145, 0
	s_cbranch_vccz .Lrgc_nh
	global_load_dwordx4 v[40:43], v[48:49], off offset:-4096
	global_load_dwordx4 v[44:47], v[48:49], off offset:-2048
.Lrgc_nh:
	s_movk_i32 s15, 0x7f0
	v_cmp_ne_u32_e32 vcc, s15, v75
	s_mov_b64 s[18:19], 0x1000
	v_lshl_add_u64 v[68:69], v[48:49], 0, s[18:19]
	s_cbranch_vccz .Lrgc_n16
	s_mov_b64 s[18:19], 0x8000
	v_lshl_add_u64 v[70:71], v[48:49], 0, s[18:19]
	global_load_dwordx4 v[142:145], v[70:71], off
.Lrgc_n16:
	s_mov_b64 s[18:19], 0x2000
	global_load_dwordx4 v[76:79], v[68:69], off offset:-4096
	global_load_dwordx4 v[80:83], v[68:69], off offset:-2048
	global_load_dwordx4 v[84:87], v[68:69], off
	global_load_dwordx4 v[88:91], v[68:69], off offset:2048
	v_lshl_add_u64 v[68:69], v[68:69], 0, s[18:19]
	global_load_dwordx4 v[92:95], v[68:69], off offset:-4096
	global_load_dwordx4 v[96:99], v[68:69], off offset:-2048
	global_load_dwordx4 v[100:103], v[68:69], off
	global_load_dwordx4 v[104:107], v[68:69], off offset:2048
	v_lshl_add_u64 v[68:69], v[68:69], 0, s[18:19]
	global_load_dwordx4 v[108:111], v[68:69], off offset:-4096
	global_load_dwordx4 v[112:115], v[68:69], off offset:-2048
	global_load_dwordx4 v[116:119], v[68:69], off
	global_load_dwordx4 v[120:123], v[68:69], off offset:2048
	v_lshl_add_u64 v[68:69], v[68:69], 0, s[18:19]
	global_load_dwordx4 v[124:127], v[68:69], off offset:-4096
	global_load_dwordx4 v[128:131], v[68:69], off offset:-2048
	global_load_dwordx4 v[132:135], v[68:69], off
	global_load_dwordx4 v[136:139], v[68:69], off offset:2048
	v_lshl_add_u64 v[50:51], s[8:9], 0, v[184:185]
	v_lshlrev_b64 v[66:67], 10, v[52:53]
	v_lshl_add_u64 v[66:67], v[50:51], 0, v[66:67]
	s_mov_b64 s[18:19], 0x1000
	s_waitcnt vmcnt(14)
	v_lshlrev_b32_e32 v146, 16, v40
	v_and_b32_e32 v147, 0xffff0000, v40
	v_lshlrev_b32_e32 v148, 16, v41
	v_and_b32_e32 v149, 0xffff0000, v41
	v_lshlrev_b32_e32 v150, 16, v42
	v_and_b32_e32 v151, 0xffff0000, v42
	v_lshlrev_b32_e32 v152, 16, v43
	v_and_b32_e32 v153, 0xffff0000, v43
	v_lshlrev_b32_e32 v154, 16, v44
	v_and_b32_e32 v155, 0xffff0000, v44
	v_lshlrev_b32_e32 v156, 16, v45
	v_and_b32_e32 v157, 0xffff0000, v45
	v_lshlrev_b32_e32 v158, 16, v46
	v_and_b32_e32 v159, 0xffff0000, v46
	v_lshlrev_b32_e32 v160, 16, v47
	v_and_b32_e32 v161, 0xffff0000, v47
	v_lshlrev_b32_e32 v162, 16, v76
	v_and_b32_e32 v163, 0xffff0000, v76
	v_lshlrev_b32_e32 v164, 16, v77
	v_and_b32_e32 v165, 0xffff0000, v77
	v_lshlrev_b32_e32 v166, 16, v78
	v_and_b32_e32 v167, 0xffff0000, v78
	v_lshlrev_b32_e32 v168, 16, v79
	v_and_b32_e32 v169, 0xffff0000, v79
	v_lshlrev_b32_e32 v170, 16, v80
	v_and_b32_e32 v171, 0xffff0000, v80
	v_lshlrev_b32_e32 v172, 16, v81
	v_and_b32_e32 v173, 0xffff0000, v81
	v_lshlrev_b32_e32 v174, 16, v82
	v_and_b32_e32 v175, 0xffff0000, v82
	v_lshlrev_b32_e32 v176, 16, v83
	v_and_b32_e32 v177, 0xffff0000, v83
	v_pk_fma_f32 v[54:55], v[24:25], v[146:147], v[20:21]
	v_pk_fma_f32 v[56:57], v[26:27], v[148:149], v[22:23]
	v_pk_fma_f32 v[58:59], v[4:5], v[150:151], v[0:1]
	v_pk_fma_f32 v[60:61], v[6:7], v[152:153], v[2:3]
	v_pk_fma_f32 v[54:55], v[28:29], v[154:155], v[54:55]
	v_pk_fma_f32 v[56:57], v[30:31], v[156:157], v[56:57]
	v_pk_fma_f32 v[58:59], v[8:9], v[158:159], v[58:59]
	v_pk_fma_f32 v[60:61], v[10:11], v[160:161], v[60:61]
	v_pk_fma_f32 v[54:55], v[36:37], v[162:163], v[54:55]
	v_pk_fma_f32 v[56:57], v[38:39], v[164:165], v[56:57]
	v_pk_fma_f32 v[58:59], v[16:17], v[166:167], v[58:59]
	v_pk_fma_f32 v[60:61], v[18:19], v[168:169], v[60:61]
	v_pk_fma_f32 v[54:55], v[32:33], v[170:171], v[54:55]
	v_pk_fma_f32 v[56:57], v[34:35], v[172:173], v[56:57]
	v_pk_fma_f32 v[58:59], v[12:13], v[174:175], v[58:59]
	v_pk_fma_f32 v[60:61], v[14:15], v[176:177], v[60:61]
	v_cvt_pk_bf16_f32 v62, v54, v55
	v_cvt_pk_bf16_f32 v63, v56, v57
	v_cvt_pk_bf16_f32 v64, v58, v59
	v_cvt_pk_bf16_f32 v65, v60, v61
	global_store_dwordx4 v[66:67], v[62:65], off
	s_waitcnt vmcnt(14)
; __device__ __forceinline__ u32x4 zero4() { unsigned z = 0; asm volatile("" : "+v"(z)); return (u32x4){z, z, z, z}; }
; __device__ __forceinline__ unsigned cvt_pk_bf16(float lo, float hi) { const f32x2_t v = {lo, hi}; const bf16x2_t b = __builtin_convertvector(v, bf16x2_t); return __builtin_bit_cast(unsigned, b); }
; __device__ __forceinline__ float lo_bf(unsigned w) { return __uint_as_float(w << 16); }
; __device__ __forceinline__ float hi_bf(unsigned w) { return __uint_as_float(w & 0xffff0000u); }
; __device__ void rg_conv_phase(const Params& p, int l) {
;     ...
;         for (int i = 0; i < 16; ++i) {
;             win[0] = win[1]; win[1] = win[2]; win[2] = win[3];
;             { const int tt = t0 + i + 1; win[3] = (tt < SEQ) ? *(const u32x4*)(src + (ptrdiff_t)(i + 1) * 1024) : zero4(); }
;             float a[8];
; #pragma unroll
;             for (int e = 0; e < 8; ++e) a[e] = bia[e];
; #pragma unroll
;             for (int k = 0; k < 4; ++k) { const u32x4 xv = win[k];
;                 a[0] += wgt[k][0] * lo_bf(xv.x); a[1] += wgt[k][1] * hi_bf(xv.x); a[2] += wgt[k][2] * lo_bf(xv.y); a[3] += wgt[k][3] * hi_bf(xv.y);
;                 a[4] += wgt[k][4] * lo_bf(xv.z); a[5] += wgt[k][5] * hi_bf(xv.z); a[6] += wgt[k][6] * lo_bf(xv.w); a[7] += wgt[k][7] * hi_bf(xv.w); }
;             u32x4 w; w.x = cvt_pk_bf16(a[0], a[1]); w.y = cvt_pk_bf16(a[2], a[3]); w.z = cvt_pk_bf16(a[4], a[5]); w.w = cvt_pk_bf16(a[6], a[7]);
;             *(u32x4*)(xc + (size_t)(tok0 + i) * 512 + c8 * 8) = w;
	v_lshlrev_b32_e32 v146, 16, v84
	v_and_b32_e32 v147, 0xffff0000, v84
	v_lshlrev_b32_e32 v148, 16, v85
	v_and_b32_e32 v149, 0xffff0000, v85
	v_lshlrev_b32_e32 v150, 16, v86
	v_and_b32_e32 v151, 0xffff0000, v86
	v_lshlrev_b32_e32 v152, 16, v87
	v_and_b32_e32 v153, 0xffff0000, v87
	v_pk_fma_f32 v[54:55], v[24:25], v[154:155], v[20:21]
	v_pk_fma_f32 v[56:57], v[26:27], v[156:157], v[22:23]
	v_pk_fma_f32 v[58:59], v[4:5], v[158:159], v[0:1]
	v_pk_fma_f32 v[60:61], v[6:7], v[160:161], v[2:3]
	v_pk_fma_f32 v[54:55], v[28:29], v[162:163], v[54:55]
	v_pk_fma_f32 v[56:57], v[30:31], v[164:165], v[56:57]
	v_pk_fma_f32 v[58:59], v[8:9], v[166:167], v[58:59]
	v_pk_fma_f32 v[60:61], v[10:11], v[168:169], v[60:61]
	v_pk_fma_f32 v[54:55], v[36:37], v[170:171], v[54:55]
	v_pk_fma_f32 v[56:57], v[38:39], v[172:173], v[56:57]
	v_pk_fma_f32 v[58:59], v[16:17], v[174:175], v[58:59]
	v_pk_fma_f32 v[60:61], v[18:19], v[176:177], v[60:61]
	v_pk_fma_f32 v[54:55], v[32:33], v[146:147], v[54:55]
	v_pk_fma_f32 v[56:57], v[34:35], v[148:149], v[56:57]
	v_pk_fma_f32 v[58:59], v[12:13], v[150:151], v[58:59]
	v_pk_fma_f32 v[60:61], v[14:15], v[152:153], v[60:61]
	v_cvt_pk_bf16_f32 v62, v54, v55
	v_cvt_pk_bf16_f32 v63, v56, v57
	v_cvt_pk_bf16_f32 v64, v58, v59
	v_cvt_pk_bf16_f32 v65, v60, v61
	global_store_dwordx4 v[66:67], v[62:65], off offset:1024
	s_waitcnt vmcnt(14)
	v_lshlrev_b32_e32 v154, 16, v88
	v_and_b32_e32 v155, 0xffff0000, v88
	v_lshlrev_b32_e32 v156, 16, v89
	v_and_b32_e32 v157, 0xffff0000, v89
	v_lshlrev_b32_e32 v158, 16, v90
	v_and_b32_e32 v159, 0xffff0000, v90
	v_lshlrev_b32_e32 v160, 16, v91
	v_and_b32_e32 v161, 0xffff0000, v91
	v_pk_fma_f32 v[54:55], v[24:25], v[162:163], v[20:21]
	v_pk_fma_f32 v[56:57], v[26:27], v[164:165], v[22:23]
	v_pk_fma_f32 v[58:59], v[4:5], v[166:167], v[0:1]
	v_pk_fma_f32 v[60:61], v[6:7], v[168:169], v[2:3]
	v_pk_fma_f32 v[54:55], v[28:29], v[170:171], v[54:55]
	v_pk_fma_f32 v[56:57], v[30:31], v[172:173], v[56:57]
	v_pk_fma_f32 v[58:59], v[8:9], v[174:175], v[58:59]
	v_pk_fma_f32 v[60:61], v[10:11], v[176:177], v[60:61]
	v_pk_fma_f32 v[54:55], v[36:37], v[146:147], v[54:55]
	v_pk_fma_f32 v[56:57], v[38:39], v[148:149], v[56:57]
	v_pk_fma_f32 v[58:59], v[16:17], v[150:151], v[58:59]
	v_pk_fma_f32 v[60:61], v[18:19], v[152:153], v[60:61]
	v_pk_fma_f32 v[54:55], v[32:33], v[154:155], v[54:55]
	v_pk_fma_f32 v[56:57], v[34:35], v[156:157], v[56:57]
	v_pk_fma_f32 v[58:59], v[12:13], v[158:159], v[58:59]
	v_pk_fma_f32 v[60:61], v[14:15], v[160:161], v[60:61]
	v_cvt_pk_bf16_f32 v62, v54, v55
	v_cvt_pk_bf16_f32 v63, v56, v57
	v_cvt_pk_bf16_f32 v64, v58, v59
	v_cvt_pk_bf16_f32 v65, v60, v61
	global_store_dwordx4 v[66:67], v[62:65], off offset:2048
	s_waitcnt vmcnt(14)
	v_lshlrev_b32_e32 v162, 16, v92
	v_and_b32_e32 v163, 0xffff0000, v92
	v_lshlrev_b32_e32 v164, 16, v93
	v_and_b32_e32 v165, 0xffff0000, v93
	v_lshlrev_b32_e32 v166, 16, v94
	v_and_b32_e32 v167, 0xffff0000, v94
	v_lshlrev_b32_e32 v168, 16, v95
	v_and_b32_e32 v169, 0xffff0000, v95
	v_pk_fma_f32 v[54:55], v[24:25], v[170:171], v[20:21]
	v_pk_fma_f32 v[56:57], v[26:27], v[172:173], v[22:23]
	v_pk_fma_f32 v[58:59], v[4:5], v[174:175], v[0:1]
	v_pk_fma_f32 v[60:61], v[6:7], v[176:177], v[2:3]
	v_pk_fma_f32 v[54:55], v[28:29], v[146:147], v[54:55]
	v_pk_fma_f32 v[56:57], v[30:31], v[148:149], v[56:57]
	v_pk_fma_f32 v[58:59], v[8:9], v[150:151], v[58:59]
	v_pk_fma_f32 v[60:61], v[10:11], v[152:153], v[60:61]
	v_pk_fma_f32 v[54:55], v[36:37], v[154:155], v[54:55]
	v_pk_fma_f32 v[56:57], v[38:39], v[156:157], v[56:57]
	v_pk_fma_f32 v[58:59], v[16:17], v[158:159], v[58:59]
	v_pk_fma_f32 v[60:61], v[18:19], v[160:161], v[60:61]
	v_pk_fma_f32 v[54:55], v[32:33], v[162:163], v[54:55]
	v_pk_fma_f32 v[56:57], v[34:35], v[164:165], v[56:57]
	v_pk_fma_f32 v[58:59], v[12:13], v[166:167], v[58:59]
	v_pk_fma_f32 v[60:61], v[14:15], v[168:169], v[60:61]
	v_cvt_pk_bf16_f32 v62, v54, v55
	v_cvt_pk_bf16_f32 v63, v56, v57
	v_cvt_pk_bf16_f32 v64, v58, v59
	v_cvt_pk_bf16_f32 v65, v60, v61
	global_store_dwordx4 v[66:67], v[62:65], off offset:3072
	v_lshl_add_u64 v[66:67], v[66:67], 0, s[18:19]
	s_waitcnt vmcnt(14)
	v_lshlrev_b32_e32 v170, 16, v96
	v_and_b32_e32 v171, 0xffff0000, v96
	v_lshlrev_b32_e32 v172, 16, v97
	v_and_b32_e32 v173, 0xffff0000, v97
	v_lshlrev_b32_e32 v174, 16, v98
	v_and_b32_e32 v175, 0xffff0000, v98
	v_lshlrev_b32_e32 v176, 16, v99
	v_and_b32_e32 v177, 0xffff0000, v99
	v_pk_fma_f32 v[54:55], v[24:25], v[146:147], v[20:21]
	v_pk_fma_f32 v[56:57], v[26:27], v[148:149], v[22:23]
	v_pk_fma_f32 v[58:59], v[4:5], v[150:151], v[0:1]
	v_pk_fma_f32 v[60:61], v[6:7], v[152:153], v[2:3]
	v_pk_fma_f32 v[54:55], v[28:29], v[154:155], v[54:55]
	v_pk_fma_f32 v[56:57], v[30:31], v[156:157], v[56:57]
	v_pk_fma_f32 v[58:59], v[8:9], v[158:159], v[58:59]
	v_pk_fma_f32 v[60:61], v[10:11], v[160:161], v[60:61]
	v_pk_fma_f32 v[54:55], v[36:37], v[162:163], v[54:55]
	v_pk_fma_f32 v[56:57], v[38:39], v[164:165], v[56:57]
	v_pk_fma_f32 v[58:59], v[16:17], v[166:167], v[58:59]
	v_pk_fma_f32 v[60:61], v[18:19], v[168:169], v[60:61]
	v_pk_fma_f32 v[54:55], v[32:33], v[170:171], v[54:55]
	v_pk_fma_f32 v[56:57], v[34:35], v[172:173], v[56:57]
	v_pk_fma_f32 v[58:59], v[12:13], v[174:175], v[58:59]
	v_pk_fma_f32 v[60:61], v[14:15], v[176:177], v[60:61]
	v_cvt_pk_bf16_f32 v62, v54, v55
	v_cvt_pk_bf16_f32 v63, v56, v57
	v_cvt_pk_bf16_f32 v64, v58, v59
	v_cvt_pk_bf16_f32 v65, v60, v61
	global_store_dwordx4 v[66:67], v[62:65], off
	s_waitcnt vmcnt(14)
; __device__ __forceinline__ u32x4 zero4() { unsigned z = 0; asm volatile("" : "+v"(z)); return (u32x4){z, z, z, z}; }
; __device__ __forceinline__ unsigned cvt_pk_bf16(float lo, float hi) { const f32x2_t v = {lo, hi}; const bf16x2_t b = __builtin_convertvector(v, bf16x2_t); return __builtin_bit_cast(unsigned, b); }
; __device__ __forceinline__ float lo_bf(unsigned w) { return __uint_as_float(w << 16); }
; __device__ __forceinline__ float hi_bf(unsigned w) { return __uint_as_float(w & 0xffff0000u); }
; __device__ void rg_conv_phase(const Params& p, int l) {
;     ...
;         for (int i = 0; i < 16; ++i) {
;             win[0] = win[1]; win[1] = win[2]; win[2] = win[3];
;             { const int tt = t0 + i + 1; win[3] = (tt < SEQ) ? *(const u32x4*)(src + (ptrdiff_t)(i + 1) * 1024) : zero4(); }
;             float a[8];
; #pragma unroll
;             for (int e = 0; e < 8; ++e) a[e] = bia[e];
; #pragma unroll
;             for (int k = 0; k < 4; ++k) { const u32x4 xv = win[k];
;                 a[0] += wgt[k][0] * lo_bf(xv.x); a[1] += wgt[k][1] * hi_bf(xv.x); a[2] += wgt[k][2] * lo_bf(xv.y); a[3] += wgt[k][3] * hi_bf(xv.y);
;                 a[4] += wgt[k][4] * lo_bf(xv.z); a[5] += wgt[k][5] * hi_bf(xv.z); a[6] += wgt[k][6] * lo_bf(xv.w); a[7] += wgt[k][7] * hi_bf(xv.w); }
;             u32x4 w; w.x = cvt_pk_bf16(a[0], a[1]); w.y = cvt_pk_bf16(a[2], a[3]); w.z = cvt_pk_bf16(a[4], a[5]); w.w = cvt_pk_bf16(a[6], a[7]);
;             *(u32x4*)(xc + (size_t)(tok0 + i) * 512 + c8 * 8) = w;
	v_lshlrev_b32_e32 v146, 16, v100
	v_and_b32_e32 v147, 0xffff0000, v100
	v_lshlrev_b32_e32 v148, 16, v101
	v_and_b32_e32 v149, 0xffff0000, v101
	v_lshlrev_b32_e32 v150, 16, v102
	v_and_b32_e32 v151, 0xffff0000, v102
	v_lshlrev_b32_e32 v152, 16, v103
	v_and_b32_e32 v153, 0xffff0000, v103
	v_pk_fma_f32 v[54:55], v[24:25], v[154:155], v[20:21]
	v_pk_fma_f32 v[56:57], v[26:27], v[156:157], v[22:23]
	v_pk_fma_f32 v[58:59], v[4:5], v[158:159], v[0:1]
	v_pk_fma_f32 v[60:61], v[6:7], v[160:161], v[2:3]
	v_pk_fma_f32 v[54:55], v[28:29], v[162:163], v[54:55]
	v_pk_fma_f32 v[56:57], v[30:31], v[164:165], v[56:57]
	v_pk_fma_f32 v[58:59], v[8:9], v[166:167], v[58:59]
	v_pk_fma_f32 v[60:61], v[10:11], v[168:169], v[60:61]
	v_pk_fma_f32 v[54:55], v[36:37], v[170:171], v[54:55]
	v_pk_fma_f32 v[56:57], v[38:39], v[172:173], v[56:57]
	v_pk_fma_f32 v[58:59], v[16:17], v[174:175], v[58:59]
	v_pk_fma_f32 v[60:61], v[18:19], v[176:177], v[60:61]
	v_pk_fma_f32 v[54:55], v[32:33], v[146:147], v[54:55]
	v_pk_fma_f32 v[56:57], v[34:35], v[148:149], v[56:57]
	v_pk_fma_f32 v[58:59], v[12:13], v[150:151], v[58:59]
	v_pk_fma_f32 v[60:61], v[14:15], v[152:153], v[60:61]
	v_cvt_pk_bf16_f32 v62, v54, v55
	v_cvt_pk_bf16_f32 v63, v56, v57
	v_cvt_pk_bf16_f32 v64, v58, v59
	v_cvt_pk_bf16_f32 v65, v60, v61
	global_store_dwordx4 v[66:67], v[62:65], off offset:1024
	s_waitcnt vmcnt(14)
	v_lshlrev_b32_e32 v154, 16, v104
	v_and_b32_e32 v155, 0xffff0000, v104
	v_lshlrev_b32_e32 v156, 16, v105
	v_and_b32_e32 v157, 0xffff0000, v105
	v_lshlrev_b32_e32 v158, 16, v106
	v_and_b32_e32 v159, 0xffff0000, v106
	v_lshlrev_b32_e32 v160, 16, v107
	v_and_b32_e32 v161, 0xffff0000, v107
	v_pk_fma_f32 v[54:55], v[24:25], v[162:163], v[20:21]
	v_pk_fma_f32 v[56:57], v[26:27], v[164:165], v[22:23]
	v_pk_fma_f32 v[58:59], v[4:5], v[166:167], v[0:1]
	v_pk_fma_f32 v[60:61], v[6:7], v[168:169], v[2:3]
	v_pk_fma_f32 v[54:55], v[28:29], v[170:171], v[54:55]
	v_pk_fma_f32 v[56:57], v[30:31], v[172:173], v[56:57]
	v_pk_fma_f32 v[58:59], v[8:9], v[174:175], v[58:59]
	v_pk_fma_f32 v[60:61], v[10:11], v[176:177], v[60:61]
	v_pk_fma_f32 v[54:55], v[36:37], v[146:147], v[54:55]
	v_pk_fma_f32 v[56:57], v[38:39], v[148:149], v[56:57]
	v_pk_fma_f32 v[58:59], v[16:17], v[150:151], v[58:59]
	v_pk_fma_f32 v[60:61], v[18:19], v[152:153], v[60:61]
	v_pk_fma_f32 v[54:55], v[32:33], v[154:155], v[54:55]
	v_pk_fma_f32 v[56:57], v[34:35], v[156:157], v[56:57]
	v_pk_fma_f32 v[58:59], v[12:13], v[158:159], v[58:59]
	v_pk_fma_f32 v[60:61], v[14:15], v[160:161], v[60:61]
	v_cvt_pk_bf16_f32 v62, v54, v55
	v_cvt_pk_bf16_f32 v63, v56, v57
	v_cvt_pk_bf16_f32 v64, v58, v59
	v_cvt_pk_bf16_f32 v65, v60, v61
	global_store_dwordx4 v[66:67], v[62:65], off offset:2048
	s_waitcnt vmcnt(14)
	v_lshlrev_b32_e32 v162, 16, v108
	v_and_b32_e32 v163, 0xffff0000, v108
	v_lshlrev_b32_e32 v164, 16, v109
	v_and_b32_e32 v165, 0xffff0000, v109
	v_lshlrev_b32_e32 v166, 16, v110
	v_and_b32_e32 v167, 0xffff0000, v110
	v_lshlrev_b32_e32 v168, 16, v111
	v_and_b32_e32 v169, 0xffff0000, v111
	v_pk_fma_f32 v[54:55], v[24:25], v[170:171], v[20:21]
	v_pk_fma_f32 v[56:57], v[26:27], v[172:173], v[22:23]
	v_pk_fma_f32 v[58:59], v[4:5], v[174:175], v[0:1]
	v_pk_fma_f32 v[60:61], v[6:7], v[176:177], v[2:3]
	v_pk_fma_f32 v[54:55], v[28:29], v[146:147], v[54:55]
	v_pk_fma_f32 v[56:57], v[30:31], v[148:149], v[56:57]
	v_pk_fma_f32 v[58:59], v[8:9], v[150:151], v[58:59]
	v_pk_fma_f32 v[60:61], v[10:11], v[152:153], v[60:61]
	v_pk_fma_f32 v[54:55], v[36:37], v[154:155], v[54:55]
	v_pk_fma_f32 v[56:57], v[38:39], v[156:157], v[56:57]
	v_pk_fma_f32 v[58:59], v[16:17], v[158:159], v[58:59]
	v_pk_fma_f32 v[60:61], v[18:19], v[160:161], v[60:61]
	v_pk_fma_f32 v[54:55], v[32:33], v[162:163], v[54:55]
	v_pk_fma_f32 v[56:57], v[34:35], v[164:165], v[56:57]
	v_pk_fma_f32 v[58:59], v[12:13], v[166:167], v[58:59]
	v_pk_fma_f32 v[60:61], v[14:15], v[168:169], v[60:61]
	v_cvt_pk_bf16_f32 v62, v54, v55
	v_cvt_pk_bf16_f32 v63, v56, v57
	v_cvt_pk_bf16_f32 v64, v58, v59
	v_cvt_pk_bf16_f32 v65, v60, v61
	global_store_dwordx4 v[66:67], v[62:65], off offset:3072
	v_lshl_add_u64 v[66:67], v[66:67], 0, s[18:19]
	s_waitcnt vmcnt(14)
	v_lshlrev_b32_e32 v170, 16, v112
	v_and_b32_e32 v171, 0xffff0000, v112
	v_lshlrev_b32_e32 v172, 16, v113
	v_and_b32_e32 v173, 0xffff0000, v113
	v_lshlrev_b32_e32 v174, 16, v114
	v_and_b32_e32 v175, 0xffff0000, v114
	v_lshlrev_b32_e32 v176, 16, v115
	v_and_b32_e32 v177, 0xffff0000, v115
	v_pk_fma_f32 v[54:55], v[24:25], v[146:147], v[20:21]
	v_pk_fma_f32 v[56:57], v[26:27], v[148:149], v[22:23]
	v_pk_fma_f32 v[58:59], v[4:5], v[150:151], v[0:1]
	v_pk_fma_f32 v[60:61], v[6:7], v[152:153], v[2:3]
	v_pk_fma_f32 v[54:55], v[28:29], v[154:155], v[54:55]
	v_pk_fma_f32 v[56:57], v[30:31], v[156:157], v[56:57]
	v_pk_fma_f32 v[58:59], v[8:9], v[158:159], v[58:59]
	v_pk_fma_f32 v[60:61], v[10:11], v[160:161], v[60:61]
	v_pk_fma_f32 v[54:55], v[36:37], v[162:163], v[54:55]
	v_pk_fma_f32 v[56:57], v[38:39], v[164:165], v[56:57]
	v_pk_fma_f32 v[58:59], v[16:17], v[166:167], v[58:59]
	v_pk_fma_f32 v[60:61], v[18:19], v[168:169], v[60:61]
	v_pk_fma_f32 v[54:55], v[32:33], v[170:171], v[54:55]
	v_pk_fma_f32 v[56:57], v[34:35], v[172:173], v[56:57]
	v_pk_fma_f32 v[58:59], v[12:13], v[174:175], v[58:59]
	v_pk_fma_f32 v[60:61], v[14:15], v[176:177], v[60:61]
	v_cvt_pk_bf16_f32 v62, v54, v55
	v_cvt_pk_bf16_f32 v63, v56, v57
	v_cvt_pk_bf16_f32 v64, v58, v59
	v_cvt_pk_bf16_f32 v65, v60, v61
	global_store_dwordx4 v[66:67], v[62:65], off
	s_waitcnt vmcnt(14)
; __device__ __forceinline__ u32x4 zero4() { unsigned z = 0; asm volatile("" : "+v"(z)); return (u32x4){z, z, z, z}; }
; __device__ __forceinline__ unsigned cvt_pk_bf16(float lo, float hi) { const f32x2_t v = {lo, hi}; const bf16x2_t b = __builtin_convertvector(v, bf16x2_t); return __builtin_bit_cast(unsigned, b); }
; __device__ __forceinline__ float lo_bf(unsigned w) { return __uint_as_float(w << 16); }
; __device__ __forceinline__ float hi_bf(unsigned w) { return __uint_as_float(w & 0xffff0000u); }
; __device__ void rg_conv_phase(const Params& p, int l) {
;     ...
;         for (int i = 0; i < 16; ++i) {
;             win[0] = win[1]; win[1] = win[2]; win[2] = win[3];
;             { const int tt = t0 + i + 1; win[3] = (tt < SEQ) ? *(const u32x4*)(src + (ptrdiff_t)(i + 1) * 1024) : zero4(); }
;             float a[8];
; #pragma unroll
;             for (int e = 0; e < 8; ++e) a[e] = bia[e];
; #pragma unroll
;             for (int k = 0; k < 4; ++k) { const u32x4 xv = win[k];
;                 a[0] += wgt[k][0] * lo_bf(xv.x); a[1] += wgt[k][1] * hi_bf(xv.x); a[2] += wgt[k][2] * lo_bf(xv.y); a[3] += wgt[k][3] * hi_bf(xv.y);
;                 a[4] += wgt[k][4] * lo_bf(xv.z); a[5] += wgt[k][5] * hi_bf(xv.z); a[6] += wgt[k][6] * lo_bf(xv.w); a[7] += wgt[k][7] * hi_bf(xv.w); }
;             u32x4 w; w.x = cvt_pk_bf16(a[0], a[1]); w.y = cvt_pk_bf16(a[2], a[3]); w.z = cvt_pk_bf16(a[4], a[5]); w.w = cvt_pk_bf16(a[6], a[7]);
;             *(u32x4*)(xc + (size_t)(tok0 + i) * 512 + c8 * 8) = w;
	v_lshlrev_b32_e32 v146, 16, v116
	v_and_b32_e32 v147, 0xffff0000, v116
	v_lshlrev_b32_e32 v148, 16, v117
	v_and_b32_e32 v149, 0xffff0000, v117
	v_lshlrev_b32_e32 v150, 16, v118
	v_and_b32_e32 v151, 0xffff0000, v118
	v_lshlrev_b32_e32 v152, 16, v119
	v_and_b32_e32 v153, 0xffff0000, v119
	v_pk_fma_f32 v[54:55], v[24:25], v[154:155], v[20:21]
	v_pk_fma_f32 v[56:57], v[26:27], v[156:157], v[22:23]
	v_pk_fma_f32 v[58:59], v[4:5], v[158:159], v[0:1]
	v_pk_fma_f32 v[60:61], v[6:7], v[160:161], v[2:3]
	v_pk_fma_f32 v[54:55], v[28:29], v[162:163], v[54:55]
	v_pk_fma_f32 v[56:57], v[30:31], v[164:165], v[56:57]
	v_pk_fma_f32 v[58:59], v[8:9], v[166:167], v[58:59]
	v_pk_fma_f32 v[60:61], v[10:11], v[168:169], v[60:61]
	v_pk_fma_f32 v[54:55], v[36:37], v[170:171], v[54:55]
	v_pk_fma_f32 v[56:57], v[38:39], v[172:173], v[56:57]
	v_pk_fma_f32 v[58:59], v[16:17], v[174:175], v[58:59]
	v_pk_fma_f32 v[60:61], v[18:19], v[176:177], v[60:61]
	v_pk_fma_f32 v[54:55], v[32:33], v[146:147], v[54:55]
	v_pk_fma_f32 v[56:57], v[34:35], v[148:149], v[56:57]
	v_pk_fma_f32 v[58:59], v[12:13], v[150:151], v[58:59]
	v_pk_fma_f32 v[60:61], v[14:15], v[152:153], v[60:61]
	v_cvt_pk_bf16_f32 v62, v54, v55
	v_cvt_pk_bf16_f32 v63, v56, v57
	v_cvt_pk_bf16_f32 v64, v58, v59
	v_cvt_pk_bf16_f32 v65, v60, v61
	global_store_dwordx4 v[66:67], v[62:65], off offset:1024
	s_waitcnt vmcnt(14)
	v_lshlrev_b32_e32 v154, 16, v120
	v_and_b32_e32 v155, 0xffff0000, v120
	v_lshlrev_b32_e32 v156, 16, v121
	v_and_b32_e32 v157, 0xffff0000, v121
	v_lshlrev_b32_e32 v158, 16, v122
	v_and_b32_e32 v159, 0xffff0000, v122
	v_lshlrev_b32_e32 v160, 16, v123
	v_and_b32_e32 v161, 0xffff0000, v123
	v_pk_fma_f32 v[54:55], v[24:25], v[162:163], v[20:21]
	v_pk_fma_f32 v[56:57], v[26:27], v[164:165], v[22:23]
	v_pk_fma_f32 v[58:59], v[4:5], v[166:167], v[0:1]
	v_pk_fma_f32 v[60:61], v[6:7], v[168:169], v[2:3]
	v_pk_fma_f32 v[54:55], v[28:29], v[170:171], v[54:55]
	v_pk_fma_f32 v[56:57], v[30:31], v[172:173], v[56:57]
	v_pk_fma_f32 v[58:59], v[8:9], v[174:175], v[58:59]
	v_pk_fma_f32 v[60:61], v[10:11], v[176:177], v[60:61]
	v_pk_fma_f32 v[54:55], v[36:37], v[146:147], v[54:55]
	v_pk_fma_f32 v[56:57], v[38:39], v[148:149], v[56:57]
	v_pk_fma_f32 v[58:59], v[16:17], v[150:151], v[58:59]
	v_pk_fma_f32 v[60:61], v[18:19], v[152:153], v[60:61]
	v_pk_fma_f32 v[54:55], v[32:33], v[154:155], v[54:55]
	v_pk_fma_f32 v[56:57], v[34:35], v[156:157], v[56:57]
	v_pk_fma_f32 v[58:59], v[12:13], v[158:159], v[58:59]
	v_pk_fma_f32 v[60:61], v[14:15], v[160:161], v[60:61]
	v_cvt_pk_bf16_f32 v62, v54, v55
	v_cvt_pk_bf16_f32 v63, v56, v57
	v_cvt_pk_bf16_f32 v64, v58, v59
	v_cvt_pk_bf16_f32 v65, v60, v61
	global_store_dwordx4 v[66:67], v[62:65], off offset:2048
	s_waitcnt vmcnt(14)
	v_lshlrev_b32_e32 v162, 16, v124
	v_and_b32_e32 v163, 0xffff0000, v124
	v_lshlrev_b32_e32 v164, 16, v125
	v_and_b32_e32 v165, 0xffff0000, v125
	v_lshlrev_b32_e32 v166, 16, v126
	v_and_b32_e32 v167, 0xffff0000, v126
	v_lshlrev_b32_e32 v168, 16, v127
	v_and_b32_e32 v169, 0xffff0000, v127
	v_pk_fma_f32 v[54:55], v[24:25], v[170:171], v[20:21]
	v_pk_fma_f32 v[56:57], v[26:27], v[172:173], v[22:23]
	v_pk_fma_f32 v[58:59], v[4:5], v[174:175], v[0:1]
	v_pk_fma_f32 v[60:61], v[6:7], v[176:177], v[2:3]
	v_pk_fma_f32 v[54:55], v[28:29], v[146:147], v[54:55]
	v_pk_fma_f32 v[56:57], v[30:31], v[148:149], v[56:57]
	v_pk_fma_f32 v[58:59], v[8:9], v[150:151], v[58:59]
	v_pk_fma_f32 v[60:61], v[10:11], v[152:153], v[60:61]
	v_pk_fma_f32 v[54:55], v[36:37], v[154:155], v[54:55]
	v_pk_fma_f32 v[56:57], v[38:39], v[156:157], v[56:57]
	v_pk_fma_f32 v[58:59], v[16:17], v[158:159], v[58:59]
	v_pk_fma_f32 v[60:61], v[18:19], v[160:161], v[60:61]
	v_pk_fma_f32 v[54:55], v[32:33], v[162:163], v[54:55]
	v_pk_fma_f32 v[56:57], v[34:35], v[164:165], v[56:57]
	v_pk_fma_f32 v[58:59], v[12:13], v[166:167], v[58:59]
	v_pk_fma_f32 v[60:61], v[14:15], v[168:169], v[60:61]
	v_cvt_pk_bf16_f32 v62, v54, v55
	v_cvt_pk_bf16_f32 v63, v56, v57
	v_cvt_pk_bf16_f32 v64, v58, v59
	v_cvt_pk_bf16_f32 v65, v60, v61
	global_store_dwordx4 v[66:67], v[62:65], off offset:3072
	v_lshl_add_u64 v[66:67], v[66:67], 0, s[18:19]
	s_waitcnt vmcnt(14)
	v_lshlrev_b32_e32 v170, 16, v128
	v_and_b32_e32 v171, 0xffff0000, v128
	v_lshlrev_b32_e32 v172, 16, v129
	v_and_b32_e32 v173, 0xffff0000, v129
	v_lshlrev_b32_e32 v174, 16, v130
	v_and_b32_e32 v175, 0xffff0000, v130
	v_lshlrev_b32_e32 v176, 16, v131
	v_and_b32_e32 v177, 0xffff0000, v131
	v_pk_fma_f32 v[54:55], v[24:25], v[146:147], v[20:21]
	v_pk_fma_f32 v[56:57], v[26:27], v[148:149], v[22:23]
	v_pk_fma_f32 v[58:59], v[4:5], v[150:151], v[0:1]
	v_pk_fma_f32 v[60:61], v[6:7], v[152:153], v[2:3]
	v_pk_fma_f32 v[54:55], v[28:29], v[154:155], v[54:55]
	v_pk_fma_f32 v[56:57], v[30:31], v[156:157], v[56:57]
	v_pk_fma_f32 v[58:59], v[8:9], v[158:159], v[58:59]
	v_pk_fma_f32 v[60:61], v[10:11], v[160:161], v[60:61]
	v_pk_fma_f32 v[54:55], v[36:37], v[162:163], v[54:55]
	v_pk_fma_f32 v[56:57], v[38:39], v[164:165], v[56:57]
	v_pk_fma_f32 v[58:59], v[16:17], v[166:167], v[58:59]
	v_pk_fma_f32 v[60:61], v[18:19], v[168:169], v[60:61]
	v_pk_fma_f32 v[54:55], v[32:33], v[170:171], v[54:55]
	v_pk_fma_f32 v[56:57], v[34:35], v[172:173], v[56:57]
	v_pk_fma_f32 v[58:59], v[12:13], v[174:175], v[58:59]
	v_pk_fma_f32 v[60:61], v[14:15], v[176:177], v[60:61]
	v_cvt_pk_bf16_f32 v62, v54, v55
	v_cvt_pk_bf16_f32 v63, v56, v57
	v_cvt_pk_bf16_f32 v64, v58, v59
	v_cvt_pk_bf16_f32 v65, v60, v61
	global_store_dwordx4 v[66:67], v[62:65], off
	s_waitcnt vmcnt(14)
; #define TIDX tid_opaque()
; __device__ __forceinline__ u32x4 zero4() { unsigned z = 0; asm volatile("" : "+v"(z)); return (u32x4){z, z, z, z}; }
; __device__ __forceinline__ unsigned cvt_pk_bf16(float lo, float hi) { const f32x2_t v = {lo, hi}; const bf16x2_t b = __builtin_convertvector(v, bf16x2_t); return __builtin_bit_cast(unsigned, b); }
; __device__ __forceinline__ float lo_bf(unsigned w) { return __uint_as_float(w << 16); }
; __device__ __forceinline__ float hi_bf(unsigned w) { return __uint_as_float(w & 0xffff0000u); }
; __device__ void rg_conv_phase(const Params& p, int l) {
;     ...
;     for (int idx = blockIdx.x * 512 + TIDX; idx < total; idx += gridDim.x * 512) {
;     ...
;         for (int i = 0; i < 16; ++i) {
;             win[0] = win[1]; win[1] = win[2]; win[2] = win[3];
;             { const int tt = t0 + i + 1; win[3] = (tt < SEQ) ? *(const u32x4*)(src + (ptrdiff_t)(i + 1) * 1024) : zero4(); }
;             float a[8];
; #pragma unroll
;             for (int e = 0; e < 8; ++e) a[e] = bia[e];
; #pragma unroll
;             for (int k = 0; k < 4; ++k) { const u32x4 xv = win[k];
;                 a[0] += wgt[k][0] * lo_bf(xv.x); a[1] += wgt[k][1] * hi_bf(xv.x); a[2] += wgt[k][2] * lo_bf(xv.y); a[3] += wgt[k][3] * hi_bf(xv.y);
;                 a[4] += wgt[k][4] * lo_bf(xv.z); a[5] += wgt[k][5] * hi_bf(xv.z); a[6] += wgt[k][6] * lo_bf(xv.w); a[7] += wgt[k][7] * hi_bf(xv.w); }
;             u32x4 w; w.x = cvt_pk_bf16(a[0], a[1]); w.y = cvt_pk_bf16(a[2], a[3]); w.z = cvt_pk_bf16(a[4], a[5]); w.w = cvt_pk_bf16(a[6], a[7]);
;             *(u32x4*)(xc + (size_t)(tok0 + i) * 512 + c8 * 8) = w;
	v_lshlrev_b32_e32 v146, 16, v132
	v_and_b32_e32 v147, 0xffff0000, v132
	v_lshlrev_b32_e32 v148, 16, v133
	v_and_b32_e32 v149, 0xffff0000, v133
	v_lshlrev_b32_e32 v150, 16, v134
	v_and_b32_e32 v151, 0xffff0000, v134
	v_lshlrev_b32_e32 v152, 16, v135
	v_and_b32_e32 v153, 0xffff0000, v135
	v_pk_fma_f32 v[54:55], v[24:25], v[154:155], v[20:21]
	v_pk_fma_f32 v[56:57], v[26:27], v[156:157], v[22:23]
	v_pk_fma_f32 v[58:59], v[4:5], v[158:159], v[0:1]
	v_pk_fma_f32 v[60:61], v[6:7], v[160:161], v[2:3]
	v_pk_fma_f32 v[54:55], v[28:29], v[162:163], v[54:55]
	v_pk_fma_f32 v[56:57], v[30:31], v[164:165], v[56:57]
	v_pk_fma_f32 v[58:59], v[8:9], v[166:167], v[58:59]
	v_pk_fma_f32 v[60:61], v[10:11], v[168:169], v[60:61]
	v_pk_fma_f32 v[54:55], v[36:37], v[170:171], v[54:55]
	v_pk_fma_f32 v[56:57], v[38:39], v[172:173], v[56:57]
	v_pk_fma_f32 v[58:59], v[16:17], v[174:175], v[58:59]
	v_pk_fma_f32 v[60:61], v[18:19], v[176:177], v[60:61]
	v_pk_fma_f32 v[54:55], v[32:33], v[146:147], v[54:55]
	v_pk_fma_f32 v[56:57], v[34:35], v[148:149], v[56:57]
	v_pk_fma_f32 v[58:59], v[12:13], v[150:151], v[58:59]
	v_pk_fma_f32 v[60:61], v[14:15], v[152:153], v[60:61]
	v_cvt_pk_bf16_f32 v62, v54, v55
	v_cvt_pk_bf16_f32 v63, v56, v57
	v_cvt_pk_bf16_f32 v64, v58, v59
	v_cvt_pk_bf16_f32 v65, v60, v61
	global_store_dwordx4 v[66:67], v[62:65], off offset:1024
	s_waitcnt vmcnt(14)
	v_lshlrev_b32_e32 v154, 16, v136
	v_and_b32_e32 v155, 0xffff0000, v136
	v_lshlrev_b32_e32 v156, 16, v137
	v_and_b32_e32 v157, 0xffff0000, v137
	v_lshlrev_b32_e32 v158, 16, v138
	v_and_b32_e32 v159, 0xffff0000, v138
	v_lshlrev_b32_e32 v160, 16, v139
	v_and_b32_e32 v161, 0xffff0000, v139
	v_pk_fma_f32 v[54:55], v[24:25], v[162:163], v[20:21]
	v_pk_fma_f32 v[56:57], v[26:27], v[164:165], v[22:23]
	v_pk_fma_f32 v[58:59], v[4:5], v[166:167], v[0:1]
	v_pk_fma_f32 v[60:61], v[6:7], v[168:169], v[2:3]
	v_pk_fma_f32 v[54:55], v[28:29], v[170:171], v[54:55]
	v_pk_fma_f32 v[56:57], v[30:31], v[172:173], v[56:57]
	v_pk_fma_f32 v[58:59], v[8:9], v[174:175], v[58:59]
	v_pk_fma_f32 v[60:61], v[10:11], v[176:177], v[60:61]
	v_pk_fma_f32 v[54:55], v[36:37], v[146:147], v[54:55]
	v_pk_fma_f32 v[56:57], v[38:39], v[148:149], v[56:57]
	v_pk_fma_f32 v[58:59], v[16:17], v[150:151], v[58:59]
	v_pk_fma_f32 v[60:61], v[18:19], v[152:153], v[60:61]
	v_pk_fma_f32 v[54:55], v[32:33], v[154:155], v[54:55]
	v_pk_fma_f32 v[56:57], v[34:35], v[156:157], v[56:57]
	v_pk_fma_f32 v[58:59], v[12:13], v[158:159], v[58:59]
	v_pk_fma_f32 v[60:61], v[14:15], v[160:161], v[60:61]
	v_cvt_pk_bf16_f32 v62, v54, v55
	v_cvt_pk_bf16_f32 v63, v56, v57
	v_cvt_pk_bf16_f32 v64, v58, v59
	v_cvt_pk_bf16_f32 v65, v60, v61
	global_store_dwordx4 v[66:67], v[62:65], off offset:2048
	s_waitcnt vmcnt(15)
	v_lshlrev_b32_e32 v162, 16, v142
	v_and_b32_e32 v163, 0xffff0000, v142
	v_lshlrev_b32_e32 v164, 16, v143
	v_and_b32_e32 v165, 0xffff0000, v143
	v_lshlrev_b32_e32 v166, 16, v144
	v_and_b32_e32 v167, 0xffff0000, v144
	v_lshlrev_b32_e32 v168, 16, v145
	v_and_b32_e32 v169, 0xffff0000, v145
	v_pk_fma_f32 v[54:55], v[24:25], v[170:171], v[20:21]
	v_pk_fma_f32 v[56:57], v[26:27], v[172:173], v[22:23]
	v_pk_fma_f32 v[58:59], v[4:5], v[174:175], v[0:1]
	v_pk_fma_f32 v[60:61], v[6:7], v[176:177], v[2:3]
	v_pk_fma_f32 v[54:55], v[28:29], v[146:147], v[54:55]
	v_pk_fma_f32 v[56:57], v[30:31], v[148:149], v[56:57]
	v_pk_fma_f32 v[58:59], v[8:9], v[150:151], v[58:59]
	v_pk_fma_f32 v[60:61], v[10:11], v[152:153], v[60:61]
	v_pk_fma_f32 v[54:55], v[36:37], v[154:155], v[54:55]
	v_pk_fma_f32 v[56:57], v[38:39], v[156:157], v[56:57]
	v_pk_fma_f32 v[58:59], v[16:17], v[158:159], v[58:59]
	v_pk_fma_f32 v[60:61], v[18:19], v[160:161], v[60:61]
	v_pk_fma_f32 v[54:55], v[32:33], v[162:163], v[54:55]
	v_pk_fma_f32 v[56:57], v[34:35], v[164:165], v[56:57]
	v_pk_fma_f32 v[58:59], v[12:13], v[166:167], v[58:59]
	v_pk_fma_f32 v[60:61], v[14:15], v[168:169], v[60:61]
	v_cvt_pk_bf16_f32 v62, v54, v55
	v_cvt_pk_bf16_f32 v63, v56, v57
	v_cvt_pk_bf16_f32 v64, v58, v59
	v_cvt_pk_bf16_f32 v65, v60, v61
	global_store_dwordx4 v[66:67], v[62:65], off offset:3072
	v_add_u32_e32 v72, s5, v72
	s_mov_b32 s15, 0x1ffff
	v_cmp_lt_i32_e32 vcc, s15, v72
	s_or_b64 s[16:17], vcc, s[16:17]
	v_add_u32_e32 v73, s14, v73
	s_andn2_b64 exec, exec, s[16:17]
	s_cbranch_execz .LBB0_274
	s_branch .LBB0_262
